# oddprep row pass: kr / gate / pos loads also issued at the top of the trip (gate bias loaded once before the loop)
# baseline (speedup 1.0000x reference)
; DEVI unsigned pk_bf16(float lo, float hi) { unsigned r; asm("v_cvt_pk_bf16_f32 %0, %1, %2" : "=v"(r) : "v"(lo), "v"(hi)); return r; }
; DEVI float bf_lo(unsigned u) { return __uint_as_float(u << 16); }
; DEVI float bf_hi(unsigned u) { return __uint_as_float(u & 0xffff0000u); }
; DEVI int otid() { int t = threadIdx.x; asm volatile("" : "+v"(t)); return t; }
; DEVI int obid() { int t = blockIdx.x; asm volatile("" : "+s"(t)); return t; }
; DEVI float wave_sum(float v) { for (int o = 32; o; o >>= 1) v += __shfl_xor(v, o); return v; }
; __device__ __forceinline__ void oddprep_phase(const Params& p) {
;   const int tid = otid(); const int lane = tid & 63, wave = (obid() * NT + tid) >> 6, nw = gridDim.x * (NT / 64);
;   bf16_t* Zo = (bf16_t*)(p.ws + OFF_Z);
;   float* G = (float*)(p.ws + OFF_GATES);
;   bf16_t* KR = (bf16_t*)(p.ws + OFF_KR);
;   float* ROPE = (float*)(p.ws + OFF_ROPE);
;   for (int r = wave; r < M; r += nw) {
;     bf16_t* zr = Zo + (size_t)r * LDZO;
;     {
;       unsigned u[3]; float ss = 0.f;
; #pragma unroll
;       for (int j = 0; j < 3; ++j) { u[j] = *(const unsigned*)(zr + 128 * j + 2 * lane); ss += bf_lo(u[j]) * bf_lo(u[j]) + bf_hi(u[j]) * bf_hi(u[j]); }
;       ss = wave_sum(ss); const float rs = rsqrtf(ss * (1.0f / 384.0f) + EPS);
; #pragma unroll
;       for (int j = 0; j < 3; ++j) { const float* gp = p.od_g_qa + 128 * j + 2 * lane; *(unsigned*)(zr + 128 * j + 2 * lane) = pk_bf16(bf_lo(u[j]) * rs * gp[0], bf_hi(u[j]) * rs * gp[1]); }
;     }
;     {
;       const uint2 u = *(const uint2*)(zr + 384 + 4 * lane);
;       float v0 = bf_lo(u.x), v1 = bf_hi(u.x), v2 = bf_lo(u.y), v3 = bf_hi(u.y);
;       float ss = wave_sum(v0 * v0 + v1 * v1 + v2 * v2 + v3 * v3); const float rs = rsqrtf(ss * (1.0f / 256.0f) + EPS);
;       const float* gp = p.od_g_kva + 4 * lane; uint2 o; o.x = pk_bf16(v0 * rs * gp[0], v1 * rs * gp[1]); o.y = pk_bf16(v2 * rs * gp[2], v3 * rs * gp[3]);
;       *(uint2*)(zr + 384 + 4 * lane) = o;
;     }
;     {
;       const int b = r / T, t = r - b * T;
;       const int pos = t < 16 ? t : p.pos[b * 4096 + (t - 16)] + 16;
;       const int i = lane & 15;
;       const float freq = exp2f(-(float)i * 0.8304820237218406f);
.LBB0_1260:
	s_or_b64 exec, exec, s[0:1]
	s_waitcnt lgkmcnt(0)
	v_mov_b32_e32 v0, v128
	v_readlane_b32 s0, v254, 22
	s_barrier
	s_nop 0
	v_lshl_add_u32 v1, s0, 9, v0
	v_ashrrev_i32_e32 v4, 6, v1
	v_cmp_gt_i32_e32 vcc, s22, v4
	s_and_saveexec_b64 s[0:1], vcc
	s_cbranch_execz .LBB0_1275
	v_cmp_lt_i32_e32 vcc, v185, v184
	s_mov_b32 s2, 0xc2fc0000
	v_and_b32_e32 v1, 63, v0
	v_cndmask_b32_e32 v5, v183, v185, vcc
	v_cmp_lt_i32_e32 vcc, v186, v184
	v_lshlrev_b32_e32 v38, 2, v5
	v_readlane_b32 s36, v253, 44
	v_cndmask_b32_e32 v5, v183, v186, vcc
	v_cmp_lt_i32_e32 vcc, v187, v184
	v_lshlrev_b32_e32 v39, 2, v5
	v_lshlrev_b32_e32 v2, 1, v1
	v_cndmask_b32_e32 v5, v183, v187, vcc
	v_cmp_lt_i32_e32 vcc, v191, v184
	v_lshlrev_b32_e32 v40, 2, v5
	v_lshlrev_b32_e32 v26, 2, v1
	v_cndmask_b32_e32 v5, v183, v191, vcc
	v_cmp_lt_i32_e32 vcc, v192, v184
	v_lshlrev_b32_e32 v41, 2, v5
	v_cmp_gt_u32_e64 s[4:5], 16, v1
	v_cndmask_b32_e32 v5, v183, v192, vcc
	v_cmp_lt_i32_e32 vcc, v190, v184
	v_lshlrev_b32_e32 v42, 2, v5
	v_lshlrev_b32_e32 v24, 3, v1
	v_cndmask_b32_e32 v5, v183, v190, vcc
	v_lshlrev_b32_e32 v43, 2, v5
	v_and_b32_e32 v5, 15, v0
	v_cvt_f32_ubyte0_e32 v5, v5
	v_mul_f32_e32 v6, 0xbf549a78, v5
	v_cmp_gt_f32_e32 vcc, s2, v6
	v_mov_b32_e32 v6, 0x42800000
	v_lshlrev_b32_e32 v0, 5, v0
	v_cndmask_b32_e32 v6, 0, v6, vcc
	v_fmac_f32_e32 v6, 0xbf549a78, v5
	v_exp_f32_e32 v5, v6
	v_not_b32_e32 v6, 63
	v_cndmask_b32_e32 v6, 0, v6, vcc
	v_cmp_gt_u32_e64 s[2:3], 32, v1
	v_ldexp_f32 v44, v5, v6
	v_cmp_gt_u32_e64 s[6:7], 8, v1
	v_lshlrev_b32_e32 v30, 4, v1
	v_readlane_b32 s40, v253, 48
	v_readlane_b32 s41, v253, 49
	v_readlane_b32 s42, v253, 50
	v_readlane_b32 s43, v253, 51
	v_and_b32_e32 v0, 0xe0, v0
	v_mov_b32_e32 v1, v130
	v_ashrrev_i32_e32 v5, 31, v4
	v_mov_b32_e32 v3, v130
	v_lshl_add_u64 v[12:13], s[40:41], 0, v[0:1]
	v_lshl_add_u64 v[14:15], s[42:43], 0, v[0:1]
	v_lshlrev_b64 v[0:1], 6, v[4:5]
	v_lshl_add_u64 v[0:1], v[0:1], 0, v[2:3]
	s_mov_b64 s[8:9], 0x17a95900
	v_mov_b32_e32 v27, v130
	v_lshl_add_u64 v[18:19], v[0:1], 0, s[8:9]
	v_lshlrev_b64 v[0:1], 7, v[4:5]
	v_lshl_add_u64 v[20:21], v[0:1], 0, v[26:27]
	v_lshlrev_b64 v[0:1], 5, v[4:5]
	v_lshl_add_u64 v[0:1], v[0:1], 0, v[26:27]
	s_mov_b64 s[8:9], 0x3710000
	v_mov_b32_e32 v25, v130
	v_readlane_b32 s38, v253, 46
	v_readlane_b32 s39, v253, 47
	v_lshl_add_u64 v[22:23], v[0:1], 0, s[8:9]
	v_mad_i64_i32 v[0:1], s[8:9], v4, s53, 0
	v_lshl_add_u64 v[6:7], s[68:69], 0, v[24:25]
	v_mov_b32_e32 v31, v130
	v_lshl_add_u64 v[10:11], s[38:39], 0, v[26:27]
	v_lshl_add_u64 v[16:17], s[66:67], 0, v[26:27]
	v_or_b32_e32 v24, v0, v24
	v_or_b32_e32 v26, v0, v26
	v_or_b32_e32 v0, v0, v2
	s_mov_b64 s[8:9], 0x7895e00
	v_lshl_add_u64 v[8:9], s[70:71], 0, v[30:31]
	v_lshl_add_u64 v[28:29], v[0:1], 0, s[8:9]
	v_mad_i64_i32 v[30:31], s[8:9], v4, s53, v[30:31]
	v_mov_b32_e32 v25, v1
	v_mov_b32_e32 v27, v1
	s_mov_b64 s[8:9], 0
	v_readlane_b32 s37, v253, 45
	v_readlane_b32 s44, v253, 52
	v_readlane_b32 s45, v253, 53
	v_readlane_b32 s46, v253, 54
	v_readlane_b32 s47, v253, 55
	v_readlane_b32 s48, v253, 56
	v_readlane_b32 s49, v253, 57
	v_readlane_b32 s50, v253, 58
	v_readlane_b32 s51, v253, 59
	global_load_dwordx2 v[64:65], v[6:7], off
	global_load_dwordx2 v[66:67], v[6:7], off offset:512
	global_load_dwordx2 v[68:69], v[6:7], off offset:1024
	global_load_dwordx4 v[72:75], v[8:9], off
	global_load_dword v70, v[10:11], off
	global_load_dwordx4 v[76:79], v[12:13], off
	global_load_dwordx4 v[80:83], v[12:13], off offset:16
	global_load_dwordx4 v[84:87], v[14:15], off
	global_load_dwordx4 v[88:91], v[14:15], off offset:16
	s_mov_b64 s[100:101], exec
	s_and_b64 exec, exec, s[6:7]
	global_load_dword v110, v[16:17], off
	s_mov_b64 exec, s[100:101]
	s_waitcnt vmcnt(0)
	s_branch .LBB0_1263

; DEVI unsigned pk_bf16(float lo, float hi) { unsigned r; asm("v_cvt_pk_bf16_f32 %0, %1, %2" : "=v"(r) : "v"(lo), "v"(hi)); return r; }
; DEVI float bf_lo(unsigned u) { return __uint_as_float(u << 16); }
; DEVI float bf_hi(unsigned u) { return __uint_as_float(u & 0xffff0000u); }
; DEVI float bf2f(bf16_t v) { return __uint_as_float(((unsigned)v) << 16); }
; DEVI bf16_t f2bf(float f) { return (bf16_t)(pk_bf16(f, 0.f) & 0xffffu); }
; __device__ __forceinline__ void oddprep_phase(const Params& p) {
;     ...
;     {
;       unsigned u[3]; float ss = 0.f;
; #pragma unroll
;       for (int j = 0; j < 3; ++j) { u[j] = *(const unsigned*)(zr + 128 * j + 2 * lane); ss += bf_lo(u[j]) * bf_lo(u[j]) + bf_hi(u[j]) * bf_hi(u[j]); }
;       ss = wave_sum(ss); const float rs = rsqrtf(ss * (1.0f / 384.0f) + EPS);
; #pragma unroll
;       for (int j = 0; j < 3; ++j) { const float* gp = p.od_g_qa + 128 * j + 2 * lane; *(unsigned*)(zr + 128 * j + 2 * lane) = pk_bf16(bf_lo(u[j]) * rs * gp[0], bf_hi(u[j]) * rs * gp[1]); }
;     }
;     {
;       const uint2 u = *(const uint2*)(zr + 384 + 4 * lane);
;       float v0 = bf_lo(u.x), v1 = bf_hi(u.x), v2 = bf_lo(u.y), v3 = bf_hi(u.y);
;       float ss = wave_sum(v0 * v0 + v1 * v1 + v2 * v2 + v3 * v3); const float rs = rsqrtf(ss * (1.0f / 256.0f) + EPS);
;       const float* gp = p.od_g_kva + 4 * lane; uint2 o; o.x = pk_bf16(v0 * rs * gp[0], v1 * rs * gp[1]); o.y = pk_bf16(v2 * rs * gp[2], v3 * rs * gp[3]);
;       *(uint2*)(zr + 384 + 4 * lane) = o;
;     }
;     {
;       const int b = r / T, t = r - b * T;
;       const int pos = t < 16 ? t : p.pos[b * 4096 + (t - 16)] + 16;
;       const int i = lane & 15;
;       const float freq = exp2f(-(float)i * 0.8304820237218406f);
;       const float ang = (float)pos * freq;
;       double rev = (double)ang * 0.15915494309189535; rev -= rint(rev);
;       const float rf = (float)rev;
;       const float cs = __builtin_amdgcn_cosf(rf), sn = __builtin_amdgcn_sinf(rf);
;       float v = lane < 32 ? bf2f(zr[640 + lane]) : 0.f;
;       const float ss = wave_sum(v * v); const float rs = rsqrtf(ss * (1.0f / 32.0f) + EPS);
;       const float kn = lane < 32 ? v * rs * p.od_g_kr[lane & 31] : 0.f;
;       const float pt = __shfl_xor(kn, 16);
;       const float o = lane < 16 ? kn * cs - pt * sn : pt * sn + kn * cs;
;       if (lane < 32) KR[(size_t)r * 32 + lane] = f2bf(o);
.LBB0_1263:
	v_readlane_b32 s16, v253, 2
	v_readlane_b32 s18, v253, 4
	v_readlane_b32 s19, v253, 5
	s_mov_b32 s10, 0x7895000
	v_readlane_b32 s17, v253, 3
	v_lshl_add_u64 v[0:1], s[18:19], 0, v[26:27]
	v_add_co_u32_e32 v0, vcc, 0x7895000, v0
	s_nop 1
	v_addc_co_u32_e32 v1, vcc, 0, v1, vcc
	global_load_dword v5, v[0:1], off offset:2304
	global_load_dword v3, v[0:1], off offset:2560
	global_load_dword v36, v[0:1], off offset:2816
	v_lshl_add_u64 v[92:93], s[18:19], 0, v[30:31]
	v_add_co_u32_e32 v92, vcc, 0x7895000, v92
	s_nop 1
	v_addc_co_u32_e32 v93, vcc, 0, v93, vcc
	global_load_dwordx4 v[96:99], v[92:93], off offset:3648
	v_add_co_u32_e32 v94, vcc, 0x1000, v92
	s_nop 1
	v_addc_co_u32_e32 v95, vcc, 0, v93, vcc
	global_load_dwordx4 v[100:103], v[94:95], off offset:576
	v_lshl_add_u64 v[94:95], s[18:19], 0, v[24:25]
	v_add_co_u32_e32 v94, vcc, 0x7895000, v94
	s_nop 1
	v_addc_co_u32_e32 v95, vcc, 0, v95, vcc
	global_load_dwordx2 v[104:105], v[94:95], off offset:3072
	s_mov_b64 s[100:101], exec
	s_and_b64 exec, exec, s[2:3]
	v_lshl_add_u64 v[106:107], s[18:19], 0, v[28:29]
	global_load_ushort v108, v[106:107], off
	s_mov_b64 exec, s[100:101]
	s_and_b64 exec, exec, s[6:7]
	v_lshl_add_u64 v[106:107], s[18:19], 0, v[22:23]
	global_load_dword v109, v[106:107], off
	s_mov_b64 exec, s[100:101]
	v_mul_hi_i32 v111, v4, s23
	v_lshrrev_b32_e32 v112, 31, v111
	v_ashrrev_i32_e32 v111, 11, v111
	v_add_u32_e32 v112, v111, v112
	v_readlane_b32 s98, v253, 30
	v_readlane_b32 s99, v253, 31
	v_mul_i32_i24_e32 v111, 0xffffeff0, v112
	v_lshl_add_u32 v111, v112, 12, v111
	v_add3_u32 v112, v4, v111, -16
	v_max_i32_e32 v112, 0, v112
	v_mov_b32_e32 v113, 0
	v_lshl_add_u64 v[112:113], v[112:113], 2, s[98:99]
	global_load_dword v114, v[112:113], off
	s_waitcnt vmcnt(8)
	v_lshlrev_b32_e32 v34, 16, v5
	s_waitcnt vmcnt(7)
	v_lshlrev_b32_e32 v2, 16, v3
	v_and_b32_e32 v3, 0xffff0000, v3
	s_waitcnt vmcnt(6)
	v_lshlrev_b32_e32 v35, 16, v36
	v_and_b32_e32 v37, 0xffff0000, v36
	v_and_b32_e32 v36, 0xffff0000, v5
	v_pk_mul_f32 v[32:33], v[2:3], v[2:3]
	v_pk_mul_f32 v[46:47], v[36:37], v[36:37]
	v_add_f32_e32 v5, v32, v33
	v_pk_fma_f32 v[46:47], v[34:35], v[34:35], v[46:47]
	s_nop 0
	v_add_f32_e32 v5, v46, v5
	v_add_f32_e32 v5, v5, v47
	ds_bpermute_b32 v32, v38, v5
	s_waitcnt lgkmcnt(0)
	v_add_f32_e32 v5, v5, v32
	ds_bpermute_b32 v32, v39, v5
	s_waitcnt lgkmcnt(0)
	v_add_f32_e32 v5, v5, v32
	ds_bpermute_b32 v32, v40, v5
	s_waitcnt lgkmcnt(0)
	v_add_f32_e32 v5, v5, v32
	ds_bpermute_b32 v32, v41, v5
	s_waitcnt lgkmcnt(0)
	v_add_f32_e32 v5, v5, v32
	ds_bpermute_b32 v32, v42, v5
	s_waitcnt lgkmcnt(0)
	v_add_f32_e32 v5, v5, v32
	ds_bpermute_b32 v32, v43, v5
	s_waitcnt lgkmcnt(0)
	v_add_f32_e32 v5, v5, v32
	v_fmamk_f32 v5, v5, 0x3b2aaaab, v132
	v_cmp_gt_f32_e32 vcc, s81, v5
	v_mul_f32_e32 v32, 0x4b800000, v5
	s_nop 0
	v_cndmask_b32_e32 v5, v5, v32, vcc
	v_rsq_f32_e32 v5, v5
	s_nop 0
	v_mul_f32_e32 v32, 0x45800000, v5
	v_cndmask_b32_e32 v5, v5, v32, vcc
	v_mul_f32_e32 v34, v5, v34
	v_mul_f32_e32 v2, v5, v2
	v_mul_f32_e32 v3, v5, v3
	s_nop 1
	v_mov_b64_e32 v[32:33], v[64:65]
	v_mul_f32_e32 v32, v32, v34
	v_mul_f32_e32 v34, v5, v36
	v_mul_f32_e32 v33, v33, v34
	v_cvt_pk_bf16_f32 v32, v32, v33
	global_store_dword v[0:1], v32, off offset:2304
	s_nop 1
	v_mov_b64_e32 v[32:33], v[66:67]
	v_mul_f32_e32 v2, v32, v2
	v_mul_f32_e32 v3, v33, v3
	v_cvt_pk_bf16_f32 v2, v2, v3
	global_store_dword v[0:1], v2, off offset:2560
	v_mul_f32_e32 v32, v5, v35
	v_mul_f32_e32 v5, v5, v37
	s_nop 1
	v_mov_b64_e32 v[2:3], v[68:69]
	v_mul_f32_e32 v2, v2, v32
	v_mul_f32_e32 v3, v3, v5
	v_cvt_pk_bf16_f32 v2, v2, v3
	global_store_dword v[0:1], v2, off offset:2816
	v_lshl_add_u64 v[0:1], s[18:19], 0, v[24:25]
	v_add_co_u32_e32 v32, vcc, s10, v0
	s_nop 1
	v_addc_co_u32_e32 v33, vcc, 0, v1, vcc
	s_waitcnt vmcnt(0)
	v_mov_b64_e32 v[0:1], v[104:105]
	v_lshlrev_b32_e32 v34, 16, v0
	v_and_b32_e32 v35, 0xffff0000, v0
	v_lshlrev_b32_e32 v37, 16, v1
	v_and_b32_e32 v36, 0xffff0000, v1
	v_pk_mul_f32 v[0:1], v[34:35], v[34:35]
	v_pk_mul_f32 v[2:3], v[36:37], v[36:37]
	v_add_f32_e32 v0, v0, v1
	v_add_f32_e32 v0, v0, v3
	v_add_f32_e32 v0, v2, v0
	ds_bpermute_b32 v1, v38, v0
	s_waitcnt lgkmcnt(0)
	v_add_f32_e32 v0, v0, v1
	ds_bpermute_b32 v1, v39, v0
	s_waitcnt lgkmcnt(0)
	v_add_f32_e32 v0, v0, v1
	ds_bpermute_b32 v1, v40, v0
	s_waitcnt lgkmcnt(0)
	v_add_f32_e32 v0, v0, v1
	ds_bpermute_b32 v1, v41, v0
	s_waitcnt lgkmcnt(0)
	v_add_f32_e32 v0, v0, v1
	ds_bpermute_b32 v1, v42, v0
	s_waitcnt lgkmcnt(0)
	v_add_f32_e32 v0, v0, v1
	ds_bpermute_b32 v1, v43, v0
	s_waitcnt lgkmcnt(0)
	v_add_f32_e32 v0, v0, v1
	v_fmamk_f32 v0, v0, 0x3b800000, v132
	v_cmp_gt_f32_e32 vcc, s81, v0
	v_mul_f32_e32 v1, 0x4b800000, v0
	s_nop 0
	v_cndmask_b32_e32 v0, v0, v1, vcc
	v_rsq_f32_e32 v0, v0
	s_nop 0
	v_mul_f32_e32 v1, 0x45800000, v0
	v_cndmask_b32_e32 v5, v0, v1, vcc
	v_mul_f32_e32 v34, v5, v34
	s_nop 1
	v_mov_b64_e32 v[0:1], v[72:73]
	v_mov_b64_e32 v[2:3], v[74:75]
	v_mul_f32_e32 v0, v0, v34
	v_mul_f32_e32 v34, v5, v35
	v_mul_f32_e32 v1, v1, v34
	v_cvt_pk_bf16_f32 v0, v0, v1
	v_mul_f32_e32 v1, v5, v37
	v_mul_f32_e32 v1, v2, v1
	v_mul_f32_e32 v2, v5, v36
	v_mul_f32_e32 v2, v3, v2
	v_cvt_pk_bf16_f32 v1, v1, v2
	global_store_dwordx2 v[32:33], v[0:1], off offset:3072
	v_mul_hi_i32 v0, v4, s23
	v_lshrrev_b32_e32 v1, 31, v0
	v_ashrrev_i32_e32 v0, 11, v0
	v_add_u32_e32 v1, v0, v1
	v_mad_i32_i24 v0, v1, s24, v4
	v_cmp_lt_i32_e32 vcc, 15, v0
	s_and_saveexec_b64 s[10:11], vcc
	s_cbranch_execz .LBB0_1265
	v_mul_i32_i24_e32 v0, 0xffffeff0, v1
	v_lshl_add_u32 v0, v1, 12, v0
	v_add3_u32 v0, v4, v0, -16
	v_readlane_b32 s36, v253, 28
	v_ashrrev_i32_e32 v1, 31, v0
	v_readlane_b32 s38, v253, 30
	v_readlane_b32 s39, v253, 31
	v_readlane_b32 s37, v253, 29
	v_readlane_b32 s40, v253, 32
	v_lshl_add_u64 v[0:1], v[0:1], 2, s[38:39]
	v_readlane_b32 s41, v253, 33
	v_readlane_b32 s42, v253, 34
	v_readlane_b32 s43, v253, 35
	v_readlane_b32 s44, v253, 36
	v_readlane_b32 s45, v253, 37
	v_readlane_b32 s46, v253, 38
	v_readlane_b32 s47, v253, 39
	v_readlane_b32 s48, v253, 40
	v_readlane_b32 s49, v253, 41
	v_readlane_b32 s50, v253, 42
	v_readlane_b32 s51, v253, 43
	s_waitcnt vmcnt(0)
	v_mov_b32_e32 v0, v114
	v_add_u32_e32 v0, 16, v0
.LBB0_1265:
	s_or_b64 exec, exec, s[10:11]
	v_mov_b32_e32 v1, 0
	v_mov_b32_e32 v2, 0
	s_and_saveexec_b64 s[10:11], s[2:3]
	s_cbranch_execz .LBB0_1267
	v_readlane_b32 s16, v253, 2
	v_readlane_b32 s18, v253, 4
	v_readlane_b32 s19, v253, 5
	v_readlane_b32 s17, v253, 3
	s_nop 0
	v_lshl_add_u64 v[2:3], s[18:19], 0, v[28:29]
	s_waitcnt vmcnt(0)
	v_mov_b32_e32 v2, v108
	v_lshlrev_b32_e32 v2, 16, v2

; DEVI unsigned pk_bf16(float lo, float hi) { unsigned r; asm("v_cvt_pk_bf16_f32 %0, %1, %2" : "=v"(r) : "v"(lo), "v"(hi)); return r; }
; DEVI float bf_lo(unsigned u) { return __uint_as_float(u << 16); }
; DEVI float bf_hi(unsigned u) { return __uint_as_float(u & 0xffff0000u); }
; DEVI float logsigmoidf_(float x) { return fminf(x, 0.f) - 0.6931471805599453f * __builtin_amdgcn_logf(1.0f + __builtin_amdgcn_exp2f(-fabsf(x) * LOG2E)); }
; __device__ __forceinline__ void oddprep_phase(const Params& p) {
;     ...
; #pragma unroll
;     for (int which = 0; which < 2; ++which) {
;       bf16_t* base = zr + (which ? 1184 : 672) + 8 * lane; const float* gg = (which ? p.od_g_fk : p.od_g_fq) + 8 * (lane & 7);
;       const uint4 u = *(const uint4*)base; const unsigned uu[4] = {u.x, u.y, u.z, u.w};
;       float v[8]; float ss = 0.f;
; #pragma unroll
;       for (int j = 0; j < 4; ++j) { v[2 * j] = bf_lo(uu[j]); v[2 * j + 1] = bf_hi(uu[j]); ss += v[2 * j] * v[2 * j] + v[2 * j + 1] * v[2 * j + 1]; }
;       ss += __shfl_xor(ss, 1); ss += __shfl_xor(ss, 2); ss += __shfl_xor(ss, 4);
;       const float rs = rsqrtf(ss * (1.0f / 64.0f) + EPS);
;       *(uint4*)base = make_uint4(pk_bf16(v[0] * rs * gg[0], v[1] * rs * gg[1]), pk_bf16(v[2] * rs * gg[2], v[3] * rs * gg[3]), pk_bf16(v[4] * rs * gg[4], v[5] * rs * gg[5]), pk_bf16(v[6] * rs * gg[6], v[7] * rs * gg[7]));
;     }
;     if (lane < 8) { float* gp = G + (size_t)r * 8 + lane; *gp = logsigmoidf_(*gp + p.od_b_f[lane]); }
.LBB0_1273:
	s_or_b64 exec, exec, s[10:11]
	v_readlane_b32 s16, v253, 2
	v_readlane_b32 s18, v253, 4
	v_readlane_b32 s19, v253, 5
	s_mov_b32 s10, 0x7896000
	v_readlane_b32 s17, v253, 3
	v_lshl_add_u64 v[0:1], s[18:19], 0, v[30:31]
	v_add_co_u32_e32 v2, vcc, 0x7895000, v0
	s_waitcnt lgkmcnt(0)
	s_nop 0
	v_addc_co_u32_e32 v3, vcc, 0, v1, vcc
	s_waitcnt vmcnt(0)
	v_mov_b64_e32 v[32:33], v[96:97]
	v_mov_b64_e32 v[34:35], v[98:99]
	v_and_b32_e32 v47, 0xffff0000, v33
	v_and_b32_e32 v46, 0xffff0000, v32
	v_lshlrev_b32_e32 v37, 16, v33
	v_lshlrev_b32_e32 v36, 16, v32
	v_pk_mul_f32 v[32:33], v[46:47], v[46:47]
	v_and_b32_e32 v51, 0xffff0000, v35
	v_and_b32_e32 v50, 0xffff0000, v34
	v_pk_fma_f32 v[32:33], v[36:37], v[36:37], v[32:33]
	v_lshlrev_b32_e32 v49, 16, v35
	v_lshlrev_b32_e32 v48, 16, v34
	v_pk_mul_f32 v[34:35], v[50:51], v[50:51]
	v_add_f32_e32 v5, v32, v33
	v_pk_fma_f32 v[34:35], v[48:49], v[48:49], v[34:35]
	s_nop 0
	v_add_f32_e32 v5, v5, v34
	v_add_f32_e32 v5, v5, v35
	ds_bpermute_b32 v32, v43, v5
	s_waitcnt lgkmcnt(0)
	v_add_f32_e32 v5, v5, v32
	ds_bpermute_b32 v32, v42, v5
	s_waitcnt lgkmcnt(0)
	v_add_f32_e32 v5, v5, v32
	ds_bpermute_b32 v32, v41, v5
	s_waitcnt lgkmcnt(0)
	v_add_f32_e32 v5, v5, v32
	v_fmamk_f32 v5, v5, 0x3c800000, v132
	v_cmp_gt_f32_e32 vcc, s81, v5
	v_mul_f32_e32 v32, 0x4b800000, v5
	s_nop 0
	v_cndmask_b32_e32 v5, v5, v32, vcc
	v_rsq_f32_e32 v5, v5
	s_nop 0
	v_mul_f32_e32 v32, 0x45800000, v5
	v_cndmask_b32_e32 v5, v5, v32, vcc
	v_mul_f32_e32 v36, v5, v36
	v_mul_f32_e32 v45, v5, v48
	s_nop 1
	v_mov_b64_e32 v[32:33], v[76:77]
	v_mov_b64_e32 v[34:35], v[78:79]
	v_mul_f32_e32 v32, v32, v36
	v_mul_f32_e32 v36, v5, v46
	v_mul_f32_e32 v33, v33, v36
	v_cvt_pk_bf16_f32 v32, v32, v33
	v_mul_f32_e32 v33, v5, v37
	v_mul_f32_e32 v33, v34, v33
	v_mul_f32_e32 v34, v5, v47
	v_mul_f32_e32 v34, v35, v34
	v_cvt_pk_bf16_f32 v33, v33, v34
	s_nop 1
	v_mov_b64_e32 v[34:35], v[80:81]
	v_mov_b64_e32 v[36:37], v[82:83]
	v_mul_f32_e32 v34, v34, v45
	v_mul_f32_e32 v45, v5, v50
	v_mul_f32_e32 v35, v35, v45
	v_cvt_pk_bf16_f32 v34, v34, v35
	v_mul_f32_e32 v35, v5, v49
	v_mul_f32_e32 v35, v36, v35
	v_mul_f32_e32 v5, v5, v51
	v_mul_f32_e32 v5, v37, v5
	v_cvt_pk_bf16_f32 v35, v35, v5
	global_store_dwordx4 v[2:3], v[32:35], off offset:3648
	s_nop 1
	v_add_co_u32_e32 v32, vcc, s10, v0
	s_nop 1
	v_addc_co_u32_e32 v33, vcc, 0, v1, vcc
	s_waitcnt vmcnt(0)
	v_mov_b64_e32 v[0:1], v[100:101]
	v_mov_b64_e32 v[2:3], v[102:103]
	v_lshlrev_b32_e32 v37, 16, v1
	v_lshlrev_b32_e32 v36, 16, v0
	v_and_b32_e32 v1, 0xffff0000, v1
	v_and_b32_e32 v0, 0xffff0000, v0
	v_pk_mul_f32 v[34:35], v[0:1], v[0:1]
	s_nop 0
	v_pk_fma_f32 v[46:47], v[36:37], v[36:37], v[34:35]
	v_lshlrev_b32_e32 v35, 16, v3
	v_lshlrev_b32_e32 v34, 16, v2
	v_and_b32_e32 v3, 0xffff0000, v3
	v_and_b32_e32 v2, 0xffff0000, v2
	v_pk_mul_f32 v[48:49], v[2:3], v[2:3]
	v_add_f32_e32 v5, v46, v47
	v_pk_fma_f32 v[48:49], v[34:35], v[34:35], v[48:49]
	s_nop 0
	v_add_f32_e32 v5, v5, v48
	v_add_f32_e32 v5, v5, v49
	ds_bpermute_b32 v45, v43, v5
	s_waitcnt lgkmcnt(0)
	v_add_f32_e32 v5, v5, v45
	ds_bpermute_b32 v45, v42, v5
	s_waitcnt lgkmcnt(0)
	v_add_f32_e32 v5, v5, v45
	ds_bpermute_b32 v45, v41, v5
	s_waitcnt lgkmcnt(0)
	v_add_f32_e32 v5, v5, v45
	v_fmamk_f32 v5, v5, 0x3c800000, v132
	v_cmp_gt_f32_e32 vcc, s81, v5
	v_mul_f32_e32 v45, 0x4b800000, v5
	s_nop 0
	v_cndmask_b32_e32 v5, v5, v45, vcc
	v_rsq_f32_e32 v5, v5
	s_nop 0
	v_mul_f32_e32 v45, 0x45800000, v5
	v_cndmask_b32_e32 v5, v5, v45, vcc
	v_mul_f32_e32 v36, v5, v36
	v_mul_f32_e32 v0, v5, v0
	v_mul_f32_e32 v1, v5, v1
	v_mul_f32_e32 v34, v5, v34
	v_mul_f32_e32 v2, v5, v2
	v_mul_f32_e32 v3, v5, v3
	s_nop 1
	v_mov_b64_e32 v[46:47], v[84:85]
	v_mov_b64_e32 v[48:49], v[86:87]
	v_mul_f32_e32 v36, v46, v36
	v_mul_f32_e32 v0, v47, v0
	v_cvt_pk_bf16_f32 v0, v36, v0
	v_mul_f32_e32 v36, v5, v37
	v_mul_f32_e32 v36, v48, v36
	v_mul_f32_e32 v1, v49, v1
	v_cvt_pk_bf16_f32 v1, v36, v1
	s_nop 1
	v_mov_b64_e32 v[46:47], v[88:89]
	v_mov_b64_e32 v[48:49], v[90:91]
	v_mul_f32_e32 v34, v46, v34
	v_mul_f32_e32 v2, v47, v2
	v_cvt_pk_bf16_f32 v2, v34, v2
	v_mul_f32_e32 v34, v5, v35
	v_mul_f32_e32 v3, v49, v3
	v_mul_f32_e32 v34, v48, v34
	v_cvt_pk_bf16_f32 v3, v34, v3
	global_store_dwordx4 v[32:33], v[0:3], off offset:576
	s_and_saveexec_b64 s[10:11], s[6:7]
	s_cbranch_execz .LBB0_1262
	v_readlane_b32 s16, v253, 2
	v_readlane_b32 s18, v253, 4
	v_readlane_b32 s19, v253, 5
	s_mov_b32 s16, 0xbfb8aa3b
	v_readlane_b32 s17, v253, 3
	v_lshl_add_u64 v[0:1], s[18:19], 0, v[22:23]
	s_waitcnt vmcnt(0)
	v_mov_b32_e32 v2, v109
	v_mov_b32_e32 v3, v110
	v_add_f32_e32 v2, v2, v3
	v_mul_f32_e64 v3, |v2|, s16
	v_exp_f32_e32 v3, v3
	v_min_f32_e32 v2, 0, v2
	v_add_f32_e32 v3, 1.0, v3
	v_log_f32_e32 v3, v3
	s_nop 0
	v_fmac_f32_e32 v2, 0xbf317218, v3
	global_store_dword v[0:1], v2, off
	s_branch .LBB0_1262
